# direct HBM->LDS loads (global_load_lds_dwordx4) for the hyena x0 row staging instead of load-to-VGPR + ds_write, on top of v50
# speedup vs baseline: 1.0042x; 1.0042x over previous
.LBB0_506:
	v_readfirstlane_b32 s37, v198
	s_lshr_b32 s37, s37, 6
	s_lshl_b32 s37, s37, 10
	s_mov_b32 s36, m0
	s_mov_b64 s[38:39], 0x200
	v_ashrrev_i32_e32 v84, 31, v77
	v_lshrrev_b32_e32 v84, 22, v84
	v_add_u32_e32 v84, v77, v84
	v_ashrrev_i32_e32 v86, 10, v84
	v_ashrrev_i32_e32 v87, 31, v86
	v_mul_i32_i24_e32 v90, 0x400, v86
	v_lshlrev_b64 v[84:85], 8, v[86:87]
	v_mov_b64_e32 v[82:83], s[8:9]
	v_lshlrev_b32_e32 v88, 3, v90
	v_lshl_add_u64 v[84:85], v[84:85], 0, s[2:3]
	v_sub_u32_e32 v88, v76, v88
	v_mad_u64_u32 v[82:83], s[6:7], v84, s95, v[82:83]
	v_ashrrev_i32_e32 v89, 31, v88
	v_mad_i32_i24 v83, v85, s95, v83
	v_lshl_add_u64 v[82:83], v[88:89], 1, v[82:83]
	v_lshl_add_u64 v[82:83], v[82:83], 0, s[38:39]
	s_mov_b32 m0, s37
	s_nop 0
	global_load_lds_dwordx4 v[82:83], off
	s_add_i32 s37, s37, 0x2000
	v_add_u32_e32 v87, 0x200, v77
	v_mov_b32_e32 v77, v87
	v_lshlrev_b32_e32 v86, 14, v86
	v_lshlrev_b32_e32 v87, 4, v90
	v_sub_u32_e32 v86, v86, v87
	v_add_u32_e32 v76, 0x1000, v76
	v_add_u32_e32 v86, v0, v86
	v_add_u32_e32 v0, 0x2000, v0
	v_ashrrev_i32_e32 v96, 31, v77
	v_lshrrev_b32_e32 v96, 22, v96
	v_add_u32_e32 v96, v77, v96
	v_ashrrev_i32_e32 v98, 10, v96
	v_ashrrev_i32_e32 v99, 31, v98
	v_mul_i32_i24_e32 v102, 0x400, v98
	v_lshlrev_b64 v[96:97], 8, v[98:99]
	v_mov_b64_e32 v[94:95], s[8:9]
	v_lshlrev_b32_e32 v100, 3, v102
	v_lshl_add_u64 v[96:97], v[96:97], 0, s[2:3]
	v_sub_u32_e32 v100, v76, v100
	v_mad_u64_u32 v[94:95], s[6:7], v96, s95, v[94:95]
	v_ashrrev_i32_e32 v101, 31, v100
	v_mad_i32_i24 v95, v97, s95, v95
	v_lshl_add_u64 v[94:95], v[100:101], 1, v[94:95]
	v_lshl_add_u64 v[94:95], v[94:95], 0, s[38:39]
	s_mov_b32 m0, s37
	s_nop 0
	global_load_lds_dwordx4 v[94:95], off
	s_add_i32 s37, s37, 0x2000
	v_add_u32_e32 v99, 0x200, v77
	v_mov_b32_e32 v77, v99
	v_lshlrev_b32_e32 v98, 14, v98
	v_lshlrev_b32_e32 v99, 4, v102
	v_sub_u32_e32 v98, v98, v99
	v_add_u32_e32 v76, 0x1000, v76
	v_add_u32_e32 v98, v0, v98
	v_add_u32_e32 v0, 0x2000, v0
	v_ashrrev_i32_e32 v108, 31, v77
	v_lshrrev_b32_e32 v108, 22, v108
	v_add_u32_e32 v108, v77, v108
	v_ashrrev_i32_e32 v110, 10, v108
	v_ashrrev_i32_e32 v111, 31, v110
	v_mul_i32_i24_e32 v114, 0x400, v110
	v_lshlrev_b64 v[108:109], 8, v[110:111]
	v_mov_b64_e32 v[106:107], s[8:9]
	v_lshlrev_b32_e32 v112, 3, v114
	v_lshl_add_u64 v[108:109], v[108:109], 0, s[2:3]
	v_sub_u32_e32 v112, v76, v112
	v_mad_u64_u32 v[106:107], s[6:7], v108, s95, v[106:107]
	v_ashrrev_i32_e32 v113, 31, v112
	v_mad_i32_i24 v107, v109, s95, v107
	v_lshl_add_u64 v[106:107], v[112:113], 1, v[106:107]
	v_lshl_add_u64 v[106:107], v[106:107], 0, s[38:39]
	s_mov_b32 m0, s37
	s_nop 0
	global_load_lds_dwordx4 v[106:107], off
	s_add_i32 s37, s37, 0x2000
	v_add_u32_e32 v111, 0x200, v77
	v_mov_b32_e32 v77, v111
	v_lshlrev_b32_e32 v110, 14, v110
	v_lshlrev_b32_e32 v111, 4, v114
	v_sub_u32_e32 v110, v110, v111
	v_add_u32_e32 v76, 0x1000, v76
	v_add_u32_e32 v110, v0, v110
	v_add_u32_e32 v0, 0x2000, v0
	v_ashrrev_i32_e32 v120, 31, v77
	v_lshrrev_b32_e32 v120, 22, v120
	v_add_u32_e32 v120, v77, v120
	v_ashrrev_i32_e32 v122, 10, v120
	v_ashrrev_i32_e32 v123, 31, v122
	v_mul_i32_i24_e32 v126, 0x400, v122
	v_lshlrev_b64 v[120:121], 8, v[122:123]
	v_mov_b64_e32 v[118:119], s[8:9]
	v_lshlrev_b32_e32 v124, 3, v126
	v_lshl_add_u64 v[120:121], v[120:121], 0, s[2:3]
	v_sub_u32_e32 v124, v76, v124
	v_mad_u64_u32 v[118:119], s[6:7], v120, s95, v[118:119]
	v_ashrrev_i32_e32 v125, 31, v124
	v_mad_i32_i24 v119, v121, s95, v119
	v_lshl_add_u64 v[118:119], v[124:125], 1, v[118:119]
	v_lshl_add_u64 v[118:119], v[118:119], 0, s[38:39]
	s_mov_b32 m0, s37
	s_nop 0
	global_load_lds_dwordx4 v[118:119], off
	s_add_i32 s37, s37, 0x2000
	v_add_u32_e32 v123, 0x200, v77
	v_mov_b32_e32 v77, v123
	v_lshlrev_b32_e32 v122, 14, v122
	v_lshlrev_b32_e32 v123, 4, v126
	v_sub_u32_e32 v122, v122, v123
	v_add_u32_e32 v76, 0x1000, v76
	v_add_u32_e32 v122, v0, v122
	v_add_u32_e32 v0, 0x2000, v0
	s_waitcnt vmcnt(0)
	s_mov_b32 m0, s36
	s_branch .LBB0_472
